# short-conv items: gate/scale row loads issued at the top of each iteration so they overlap the three tap round trips
# baseline (speedup 1.0000x reference)
.LBB0_523:
	s_or_b64 exec, exec, s[18:19]
	s_movk_i32 s0, 0xd000
	s_addk_i32 s2, 0x100
	s_cmpk_eq_i32 s2, 0x800
	s_waitcnt vmcnt(0)
	v_mov_b32_e32 v2, v42
	v_mov_b32_e32 v3, v43
	v_mov_b32_e32 v4, v44
	v_mov_b32_e32 v5, v45
	v_mov_b32_e32 v6, v46
	v_mov_b32_e32 v7, v47
	v_mov_b32_e32 v8, v48
	v_mov_b32_e32 v9, v49
	v_lshlrev_b32_e32 v32, 16, v2
	v_and_b32_e32 v33, 0xffff0000, v2
	v_pk_mul_f32 v[28:29], v[28:29], v[32:33]
	v_lshlrev_b32_e32 v19, 16, v6
	v_and_b32_e32 v6, 0xffff0000, v6
	v_mul_f32_e32 v30, 0xbfb8aa3b, v19
	v_mul_f32_e32 v2, 0xbfb8aa3b, v6
	v_exp_f32_e32 v30, v30
	v_exp_f32_e32 v31, v2
	s_nop 0
	v_pk_add_f32 v[30:31], v[30:31], 1.0 op_sel_hi:[1,0]
	s_nop 0
	v_div_scale_f32 v2, s[18:19], v31, v31, v6
	v_rcp_f32_e32 v32, v2
	s_nop 0
	v_fma_f32 v33, -v2, v32, 1.0
	v_fmac_f32_e32 v32, v33, v32
	v_div_scale_f32 v33, vcc, v6, v31, v6
	v_mul_f32_e32 v34, v33, v32
	v_fma_f32 v35, -v2, v34, v33
	v_fmac_f32_e32 v34, v35, v32
	v_fma_f32 v2, -v2, v34, v33
	v_div_fmas_f32 v2, v2, v32, v34
	v_div_fixup_f32 v31, v2, v31, v6
	v_div_scale_f32 v2, s[18:19], v30, v30, v19
	v_rcp_f32_e32 v6, v2
	s_nop 0
	v_fma_f32 v32, -v2, v6, 1.0
	v_fmac_f32_e32 v6, v32, v6
	v_div_scale_f32 v32, vcc, v19, v30, v19
	v_mul_f32_e32 v33, v32, v6
	v_fma_f32 v34, -v2, v33, v32
	v_fmac_f32_e32 v33, v34, v6
	v_fma_f32 v2, -v2, v33, v32
	v_div_fmas_f32 v2, v2, v6, v33
	v_div_fixup_f32 v30, v2, v30, v19
	v_pk_mul_f32 v[28:29], v[28:29], v[30:31]
	v_lshlrev_b32_e32 v19, 16, v7
	v_and_b32_e32 v30, 0xffff0000, v7
	v_cvt_pk_bf16_f32 v2, v28, v29
	v_mul_f32_e32 v6, 0xbfb8aa3b, v19
	v_lshlrev_b32_e32 v28, 16, v3
	v_and_b32_e32 v29, 0xffff0000, v3
	v_mul_f32_e32 v3, 0xbfb8aa3b, v30
	v_exp_f32_e32 v6, v6
	v_exp_f32_e32 v7, v3
	v_pk_mul_f32 v[26:27], v[26:27], v[28:29]
	v_pk_add_f32 v[6:7], v[6:7], 1.0 op_sel_hi:[1,0]
	s_nop 0
	v_div_scale_f32 v3, s[18:19], v7, v7, v30
	v_rcp_f32_e32 v28, v3
	s_nop 0
	v_fma_f32 v29, -v3, v28, 1.0
	v_fmac_f32_e32 v28, v29, v28
	v_div_scale_f32 v29, vcc, v30, v7, v30
	v_mul_f32_e32 v31, v29, v28
	v_fma_f32 v32, -v3, v31, v29
	v_fmac_f32_e32 v31, v32, v28
	v_fma_f32 v3, -v3, v31, v29
	v_div_fmas_f32 v3, v3, v28, v31
	v_div_fixup_f32 v7, v3, v7, v30
	v_div_scale_f32 v3, s[18:19], v6, v6, v19
	v_rcp_f32_e32 v28, v3
	s_nop 0
	v_fma_f32 v29, -v3, v28, 1.0
	v_fmac_f32_e32 v28, v29, v28
	v_div_scale_f32 v29, vcc, v19, v6, v19
	v_mul_f32_e32 v30, v29, v28
	v_fma_f32 v31, -v3, v30, v29
	v_fmac_f32_e32 v30, v31, v28
	v_fma_f32 v3, -v3, v30, v29
	v_div_fmas_f32 v3, v3, v28, v30
	v_div_fixup_f32 v6, v3, v6, v19
	v_pk_mul_f32 v[6:7], v[26:27], v[6:7]
	v_lshlrev_b32_e32 v19, 16, v8
	v_cvt_pk_bf16_f32 v3, v6, v7
	v_and_b32_e32 v8, 0xffff0000, v8
	v_mul_f32_e32 v6, 0xbfb8aa3b, v19
	v_exp_f32_e32 v26, v6
	v_lshlrev_b32_e32 v6, 16, v4
	v_and_b32_e32 v7, 0xffff0000, v4
	v_mul_f32_e32 v4, 0xbfb8aa3b, v8
	v_exp_f32_e32 v27, v4
	v_pk_mul_f32 v[6:7], v[24:25], v[6:7]
	v_pk_add_f32 v[24:25], v[26:27], 1.0 op_sel_hi:[1,0]
	s_nop 0
	v_div_scale_f32 v4, s[18:19], v25, v25, v8
	v_rcp_f32_e32 v26, v4
	s_nop 0
	v_fma_f32 v27, -v4, v26, 1.0
	v_fmac_f32_e32 v26, v27, v26
	v_div_scale_f32 v27, vcc, v8, v25, v8
	v_mul_f32_e32 v28, v27, v26
	v_fma_f32 v29, -v4, v28, v27
	v_fmac_f32_e32 v28, v29, v26
	v_fma_f32 v4, -v4, v28, v27
	v_div_fmas_f32 v4, v4, v26, v28
	v_div_fixup_f32 v25, v4, v25, v8
	v_div_scale_f32 v4, s[18:19], v24, v24, v19
	v_rcp_f32_e32 v8, v4
	s_nop 0
	v_fma_f32 v26, -v4, v8, 1.0
	v_fmac_f32_e32 v8, v26, v8
	v_div_scale_f32 v26, vcc, v19, v24, v19
	v_mul_f32_e32 v27, v26, v8
	v_fma_f32 v28, -v4, v27, v26
	v_fmac_f32_e32 v27, v28, v8
	v_fma_f32 v4, -v4, v27, v26
	v_div_fmas_f32 v4, v4, v8, v27
	v_div_fixup_f32 v24, v4, v24, v19
	v_pk_mul_f32 v[6:7], v[6:7], v[24:25]
	v_lshlrev_b32_e32 v19, 16, v9
	v_and_b32_e32 v24, 0xffff0000, v9
	v_cvt_pk_bf16_f32 v4, v6, v7
	v_mul_f32_e32 v6, 0xbfb8aa3b, v19
	v_lshlrev_b32_e32 v8, 16, v5
	v_and_b32_e32 v9, 0xffff0000, v5
	v_mul_f32_e32 v5, 0xbfb8aa3b, v24
	v_exp_f32_e32 v6, v6
	v_exp_f32_e32 v7, v5
	v_pk_mul_f32 v[8:9], v[22:23], v[8:9]
	v_pk_add_f32 v[6:7], v[6:7], 1.0 op_sel_hi:[1,0]
	s_nop 0
	v_div_scale_f32 v5, s[18:19], v7, v7, v24
	v_rcp_f32_e32 v22, v5
	s_nop 0
	v_fma_f32 v23, -v5, v22, 1.0
	v_fmac_f32_e32 v22, v23, v22
	v_div_scale_f32 v23, vcc, v24, v7, v24
	v_mul_f32_e32 v25, v23, v22
	v_fma_f32 v26, -v5, v25, v23
	v_fmac_f32_e32 v25, v26, v22
	v_fma_f32 v5, -v5, v25, v23
	v_div_fmas_f32 v5, v5, v22, v25
	v_div_fixup_f32 v7, v5, v7, v24
	v_div_scale_f32 v5, s[18:19], v6, v6, v19
	v_rcp_f32_e32 v22, v5
	s_nop 0
	v_fma_f32 v23, -v5, v22, 1.0
	v_fmac_f32_e32 v22, v23, v22
	v_div_scale_f32 v23, vcc, v19, v6, v19
	v_mul_f32_e32 v24, v23, v22
	v_fma_f32 v25, -v5, v24, v23
	v_fmac_f32_e32 v24, v25, v22
	v_fma_f32 v5, -v5, v24, v23
	v_div_fmas_f32 v5, v5, v22, v24
	v_div_fixup_f32 v6, v5, v6, v19
	v_pk_mul_f32 v[6:7], v[8:9], v[6:7]
	s_nop 0
	v_cvt_pk_bf16_f32 v5, v6, v7
	v_mad_i64_i32 v[6:7], s[18:19], v18, s0, v[20:21]
	v_lshl_add_u64 v[6:7], v[6:7], 0, v[0:1]
	v_add_co_u32_e32 v6, vcc, 0x13200000, v6
	s_nop 1
	v_addc_co_u32_e32 v7, vcc, 0, v7, vcc
	global_store_dwordx4 v[6:7], v[2:5], off offset:2048
	s_cbranch_scc1 .LBB0_530
.LBB0_524:
	v_add_u32_e32 v0, s2, v11
	v_ashrrev_i32_e32 v0, 7, v0
	s_waitcnt vmcnt(3)
	v_add_u32_e32 v18, s1, v0
	v_cmp_gt_i32_e32 vcc, s66, v18
	v_ashrrev_i32_e32 v19, 31, v18
	v_lshlrev_b64 v[2:3], 14, v[18:19]
	v_cndmask_b32_e32 v0, v222, v223, vcc
	v_and_b32_e32 v5, v0, v18
	v_cndmask_b32_e32 v4, v224, v225, vcc
	v_lshl_add_u64 v[20:21], s[4:5], 0, v[2:3]
	v_lshlrev_b32_e32 v50, 1, v10
	v_mov_b32_e32 v51, 0
	v_lshl_add_u64 v[50:51], v[20:21], 0, v[50:51]
	v_add_co_u32_e32 v52, vcc, 0x2000, v50
	s_nop 1
	v_addc_co_u32_e32 v53, vcc, 0, v51, vcc
	v_add_co_u32_e32 v50, vcc, s95, v50
	global_load_dwordx4 v[42:45], v[52:53], off offset:2048
	s_nop 0
	v_addc_co_u32_e32 v51, vcc, 0, v51, vcc
	global_load_dwordx4 v[46:49], v[50:51], off offset:2048
	v_add_u32_e32 v0, -1, v5
	v_mov_b32_e32 v2, 0
	v_cmp_lt_u32_e32 vcc, v0, v4
	v_lshlrev_b32_e32 v0, 1, v10
	v_mov_b32_e32 v3, 0
	v_mov_b32_e32 v28, 0
	v_mov_b32_e32 v29, 0
	v_mov_b32_e32 v26, 0
	v_mov_b32_e32 v27, v2
	v_mov_b32_e32 v24, v2
	v_mov_b32_e32 v25, v2
	v_mov_b32_e32 v22, 0
	v_mov_b32_e32 v23, 0
	s_and_saveexec_b64 s[18:19], vcc
	s_cbranch_execz .LBB0_526
	v_lshl_add_u64 v[2:3], v[20:21], 0, v[0:1]
	v_add_co_u32_e32 v6, vcc, 0xffffe000, v2
	s_nop 1
	v_addc_co_u32_e32 v7, vcc, -1, v3, vcc
	global_load_dwordx4 v[6:9], v[6:7], off
	s_nop 0
	global_load_dwordx4 v[30:33], v[2:3], off offset:-4096
	global_load_dwordx4 v[34:37], v[12:13], off offset:16
	global_load_dwordx4 v[22:25], v[12:13], off
	s_waitcnt vmcnt(3)
	v_lshlrev_b32_e32 v2, 16, v6
	v_and_b32_e32 v3, 0xffff0000, v6
	s_waitcnt vmcnt(2)
	v_lshlrev_b32_e32 v6, 16, v31
	s_waitcnt vmcnt(0)
	v_pk_mul_f32 v[2:3], v[22:23], v[2:3]
	v_lshlrev_b32_e32 v22, 16, v30
	v_and_b32_e32 v23, 0xffff0000, v30
	v_pk_fma_f32 v[28:29], v[2:3], v[22:23], 0 op_sel_hi:[1,1,0]
	v_lshlrev_b32_e32 v2, 16, v7
	v_and_b32_e32 v3, 0xffff0000, v7
	v_pk_mul_f32 v[2:3], v[24:25], v[2:3]
	v_and_b32_e32 v7, 0xffff0000, v31
	v_pk_fma_f32 v[26:27], v[2:3], v[6:7], 0 op_sel_hi:[1,1,0]
	v_lshlrev_b32_e32 v2, 16, v8
	v_and_b32_e32 v3, 0xffff0000, v8
	v_pk_mul_f32 v[2:3], v[34:35], v[2:3]
	v_lshlrev_b32_e32 v6, 16, v32
	v_and_b32_e32 v7, 0xffff0000, v32
	v_pk_fma_f32 v[24:25], v[2:3], v[6:7], 0 op_sel_hi:[1,1,0]
	v_lshlrev_b32_e32 v2, 16, v9
	v_and_b32_e32 v3, 0xffff0000, v9
	v_pk_mul_f32 v[2:3], v[36:37], v[2:3]
	v_lshlrev_b32_e32 v6, 16, v33
	v_and_b32_e32 v7, 0xffff0000, v33
	v_pk_fma_f32 v[2:3], v[2:3], v[6:7], 0 op_sel_hi:[1,1,0]
	s_nop 0
	v_mov_b32_e32 v22, v2
	v_mov_b32_e32 v23, v3
